# pipelined sample up-projection on top of dual-half band attention, without the memory-item rebalance
# baseline (speedup 1.0000x reference)
; DI void p2_mixers(const Params& p, LAS unsigned char* lds) {
;     ...
;         for (int k = 0;; ++k) {
;             int it;
;             if (NGW == 2048) { if (k >= 2) break; it = k ? m1 : m0; if (it < 0) continue; }
;             else { it = gw + k * NGW; if (it >= 2176) break; }
.LBB0_982:
	s_and_b64 vcc, exec, s[12:13]
	s_cbranch_vccz .LBB0_987
	s_mov_b32 s101, -1
	s_branch .Lat_mem_go
	s_lshr_b32 s12, s48, 8
	s_and_b32 s13, s48, 0xff
	s_cmpk_ge_u32 s13, 0x80
	s_cbranch_scc0 .Lat_mem_go
	s_add_i32 s14, s48, 0xffffff00
	s_cmp_eq_u32 s39, s14
	s_cbranch_scc0 .Lat_mem_go
	s_cmp_eq_u32 s12, 5
	s_cbranch_scc1 .Lat_ret_mem
	s_cmp_eq_u32 s12, 7
	s_cbranch_scc0 .Lat_mem_go
	s_add_i32 s101, s13, 0x400
